# input-projection GEMM phase: co-resident block start stagger doubled (s_sleep 44)
# baseline (speedup 1.0000x reference)
.LBB0_277:
	s_or_b64 exec, exec, s[0:1]
	s_and_b32 s0, s33, 1
	s_bitcmp1_b32 s33, 0
	s_cselect_b64 s[2:3], -1, 0
	v_writelane_b32 v246, s2, 26
	s_cmp_eq_u32 s0, 0
	s_waitcnt lgkmcnt(0)
	s_barrier
	v_writelane_b32 v246, s3, 27
	s_cbranch_scc1 .LBB0_279
	s_sleep 44
